# P4 epilogue: residual x loads with the nontemporal hint (read once)
# speedup vs baseline: 1.0146x; 1.0146x over previous
.LBB0_675:
	s_lshl_b32 s38, s4, 8
	v_add_u32_e32 v128, s38, v157
	v_ashrrev_i32_e32 v129, 31, v128
	s_lshl_b32 s6, s55, 8
	v_lshlrev_b64 v[128:129], 11, v[128:129]
	s_ashr_i32 s7, s6, 31
	v_lshl_add_u64 v[178:179], v[128:129], 0, s[6:7]
	v_or_b32_e32 v178, v178, v156
	v_lshl_add_u64 v[128:129], v[178:179], 2, s[8:9]
	global_load_dwordx4 v[162:165], v[128:129], off nt
	global_load_dwordx4 v[170:173], v[128:129], off offset:16 nt
	global_load_dwordx4 v[192:195], v[128:129], off offset:512 nt
	global_load_dwordx4 v[196:199], v[128:129], off offset:528 nt
	v_lshl_add_u64 v[182:183], v[128:129], 0, s[16:17]
	flat_load_dwordx4 v[140:143], v[182:183] nt
	flat_load_dwordx4 v[136:139], v[182:183] offset:16 nt
	flat_load_dwordx4 v[132:135], v[182:183] offset:512 nt
	flat_load_dwordx4 v[128:131], v[182:183] offset:528 nt
	v_and_b32_e32 v167, 64, v187
	v_xor_b32_e32 v166, 16, v187
	v_add_u32_e32 v180, 64, v167
	v_cmp_lt_i32_e32 vcc, v166, v180
	s_ashr_i32 s39, s38, 31
	s_waitcnt vmcnt(0)
	v_pk_add_f32 v[168:169], v[126:127], v[164:165]
	v_cndmask_b32_e32 v166, v187, v166, vcc
	v_lshlrev_b32_e32 v191, 2, v166
	v_pk_add_f32 v[176:177], v[124:125], v[162:163]
	v_pk_add_f32 v[166:167], v[122:123], v[172:173]
	v_pk_add_f32 v[174:175], v[120:121], v[170:171]
	v_pk_add_f32 v[164:165], v[118:119], v[194:195]
	v_pk_add_f32 v[172:173], v[116:117], v[192:193]
	v_pk_add_f32 v[162:163], v[114:115], v[198:199]
	v_pk_add_f32 v[170:171], v[112:113], v[196:197]
	v_mul_f32_e32 v112, v177, v177
	v_mul_f32_e32 v113, v169, v169
	v_mul_f32_e32 v114, v175, v175
	v_mul_f32_e32 v115, v167, v167
	v_mul_f32_e32 v116, v173, v173
	v_mul_f32_e32 v117, v165, v165
	v_fmac_f32_e32 v112, v176, v176
	v_fmac_f32_e32 v113, v168, v168
	v_fmac_f32_e32 v114, v174, v174
	v_fmac_f32_e32 v115, v166, v166
	v_mul_f32_e32 v118, v171, v171
	v_mul_f32_e32 v119, v163, v163
	v_fmac_f32_e32 v116, v172, v172
	v_fmac_f32_e32 v117, v164, v164
	v_add_f32_e32 v112, v112, v113
	v_add_f32_e32 v113, v114, v115
	v_fmac_f32_e32 v118, v170, v170
	v_fmac_f32_e32 v119, v162, v162
	v_add_f32_e32 v114, v116, v117
	v_add_f32_e32 v112, v112, v113
	v_add_f32_e32 v115, v118, v119
	v_add_f32_e32 v112, v112, v114
	v_add_f32_e32 v112, v112, v115
	ds_bpermute_b32 v113, v191, v112
	v_xor_b32_e32 v114, 32, v187
	v_cmp_lt_i32_e32 vcc, v114, v180
	v_lshl_add_u64 v[180:181], s[38:39], 2, v[152:153]
	s_waitcnt lgkmcnt(0)
	v_add_f32_e32 v112, v112, v113
	v_cndmask_b32_e32 v114, v187, v114, vcc
	v_lshlrev_b32_e32 v192, 2, v114
	ds_bpermute_b32 v113, v192, v112
	s_and_saveexec_b64 s[38:39], s[0:1]
	s_cbranch_execz .LBB0_677
	s_waitcnt lgkmcnt(0)
	v_add_f32_e32 v112, v112, v113
	global_atomic_add_f32 v[180:181], v112, off
.LBB0_677:
	s_or_b64 exec, exec, s[38:39]
	v_lshl_add_u64 v[182:183], v[182:183], 0, s[16:17]
	v_pk_add_f32 v[142:143], v[110:111], v[142:143]
	v_pk_add_f32 v[140:141], v[108:109], v[140:141]
	v_pk_add_f32 v[138:139], v[106:107], v[138:139]
	flat_load_dwordx4 v[124:127], v[182:183] nt
	flat_load_dwordx4 v[120:123], v[182:183] offset:16 nt
	flat_load_dwordx4 v[116:119], v[182:183] offset:512 nt
	s_waitcnt lgkmcnt(0)
	flat_load_dwordx4 v[112:115], v[182:183] offset:528 nt
	v_pk_add_f32 v[136:137], v[104:105], v[136:137]
	v_mul_f32_e32 v108, v141, v141
	v_mul_f32_e32 v109, v143, v143
	v_mul_f32_e32 v104, v137, v137
	v_mul_f32_e32 v105, v139, v139
	v_pk_add_f32 v[134:135], v[102:103], v[134:135]
	v_pk_add_f32 v[132:133], v[100:101], v[132:133]
	v_fmac_f32_e32 v108, v140, v140
	v_fmac_f32_e32 v109, v142, v142
	v_fmac_f32_e32 v104, v136, v136
	v_fmac_f32_e32 v105, v138, v138
	v_mul_f32_e32 v100, v133, v133
	v_mul_f32_e32 v101, v135, v135
	v_pk_add_f32 v[130:131], v[98:99], v[130:131]
	v_pk_add_f32 v[128:129], v[96:97], v[128:129]
	v_add_f32_e32 v108, v108, v109
	v_add_f32_e32 v104, v104, v105
	v_fmac_f32_e32 v100, v132, v132
	v_fmac_f32_e32 v101, v134, v134
	v_mul_f32_e32 v96, v129, v129
	v_mul_f32_e32 v97, v131, v131
	v_add_f32_e32 v104, v108, v104
	v_add_f32_e32 v100, v100, v101
	v_fmac_f32_e32 v96, v128, v128
	v_fmac_f32_e32 v97, v130, v130
	v_add_f32_e32 v100, v104, v100
	v_add_f32_e32 v96, v96, v97
	v_add_f32_e32 v96, v100, v96
	ds_bpermute_b32 v97, v191, v96
	s_waitcnt lgkmcnt(0)
	v_add_f32_e32 v96, v96, v97
	ds_bpermute_b32 v97, v192, v96
	s_and_saveexec_b64 s[38:39], s[0:1]
	s_cbranch_execz .LBB0_679
	s_waitcnt lgkmcnt(0)
	v_add_f32_e32 v96, v96, v97
	global_atomic_add_f32 v[180:181], v96, off offset:64
.LBB0_679:
	s_or_b64 exec, exec, s[38:39]
	v_lshl_add_u64 v[182:183], v[182:183], 0, s[16:17]
	s_waitcnt vmcnt(0)
	v_pk_add_f32 v[126:127], v[94:95], v[126:127]
	v_pk_add_f32 v[124:125], v[92:93], v[124:125]
	v_pk_add_f32 v[122:123], v[90:91], v[122:123]
	flat_load_dwordx4 v[108:111], v[182:183] nt
	flat_load_dwordx4 v[104:107], v[182:183] offset:16 nt
	flat_load_dwordx4 v[100:103], v[182:183] offset:512 nt
	s_waitcnt lgkmcnt(0)
	flat_load_dwordx4 v[96:99], v[182:183] offset:528 nt
	v_pk_add_f32 v[120:121], v[88:89], v[120:121]
	v_mul_f32_e32 v92, v125, v125
	v_mul_f32_e32 v93, v127, v127
	v_mul_f32_e32 v88, v121, v121
	v_mul_f32_e32 v89, v123, v123
	v_pk_add_f32 v[118:119], v[86:87], v[118:119]
	v_pk_add_f32 v[116:117], v[84:85], v[116:117]
	v_fmac_f32_e32 v92, v124, v124
	v_fmac_f32_e32 v93, v126, v126
	v_fmac_f32_e32 v88, v120, v120
	v_fmac_f32_e32 v89, v122, v122
	v_mul_f32_e32 v84, v117, v117
	v_mul_f32_e32 v85, v119, v119
	v_pk_add_f32 v[114:115], v[82:83], v[114:115]
	v_pk_add_f32 v[112:113], v[80:81], v[112:113]
	v_add_f32_e32 v92, v92, v93
	v_add_f32_e32 v88, v88, v89
	v_fmac_f32_e32 v84, v116, v116
	v_fmac_f32_e32 v85, v118, v118
	v_mul_f32_e32 v80, v113, v113
	v_mul_f32_e32 v81, v115, v115
	v_add_f32_e32 v88, v92, v88
	v_add_f32_e32 v84, v84, v85
	v_fmac_f32_e32 v80, v112, v112
	v_fmac_f32_e32 v81, v114, v114
	v_add_f32_e32 v84, v88, v84
	v_add_f32_e32 v80, v80, v81
	v_add_f32_e32 v80, v84, v80
	ds_bpermute_b32 v81, v191, v80
	s_waitcnt lgkmcnt(0)
	v_add_f32_e32 v80, v80, v81
	ds_bpermute_b32 v81, v192, v80
	s_and_saveexec_b64 s[38:39], s[0:1]
	s_cbranch_execz .LBB0_681
	s_waitcnt lgkmcnt(0)
	v_add_f32_e32 v80, v80, v81
	global_atomic_add_f32 v[180:181], v80, off offset:128
.LBB0_681:
	s_or_b64 exec, exec, s[38:39]
	v_lshl_add_u64 v[182:183], v[182:183], 0, s[20:21]
	s_waitcnt vmcnt(0)
	v_pk_add_f32 v[110:111], v[78:79], v[110:111]
	v_pk_add_f32 v[108:109], v[76:77], v[108:109]
	v_pk_add_f32 v[106:107], v[74:75], v[106:107]
	flat_load_dwordx4 v[92:95], v[182:183] nt
	flat_load_dwordx4 v[88:91], v[182:183] offset:16 nt
	flat_load_dwordx4 v[84:87], v[182:183] offset:512 nt
	s_waitcnt lgkmcnt(0)
	flat_load_dwordx4 v[80:83], v[182:183] offset:528 nt
	v_pk_add_f32 v[104:105], v[72:73], v[104:105]
	v_mul_f32_e32 v76, v109, v109
	v_mul_f32_e32 v77, v111, v111
	v_mul_f32_e32 v72, v105, v105
	v_mul_f32_e32 v73, v107, v107
	v_pk_add_f32 v[102:103], v[70:71], v[102:103]
	v_pk_add_f32 v[100:101], v[68:69], v[100:101]
	v_fmac_f32_e32 v76, v108, v108
	v_fmac_f32_e32 v77, v110, v110
	v_fmac_f32_e32 v72, v104, v104
	v_fmac_f32_e32 v73, v106, v106
	v_mul_f32_e32 v68, v101, v101
	v_mul_f32_e32 v69, v103, v103
	v_pk_add_f32 v[98:99], v[66:67], v[98:99]
	v_pk_add_f32 v[96:97], v[64:65], v[96:97]
	v_add_f32_e32 v76, v76, v77
	v_add_f32_e32 v72, v72, v73
	v_fmac_f32_e32 v68, v100, v100
	v_fmac_f32_e32 v69, v102, v102
	v_mul_f32_e32 v64, v97, v97
	v_mul_f32_e32 v65, v99, v99
	v_add_f32_e32 v72, v76, v72
	v_add_f32_e32 v68, v68, v69
	v_fmac_f32_e32 v64, v96, v96
	v_fmac_f32_e32 v65, v98, v98
	v_add_f32_e32 v68, v72, v68
	v_add_f32_e32 v64, v64, v65
	v_add_f32_e32 v64, v68, v64
	ds_bpermute_b32 v65, v191, v64
	s_waitcnt lgkmcnt(0)
	v_add_f32_e32 v64, v64, v65
	ds_bpermute_b32 v65, v192, v64
	s_and_saveexec_b64 s[38:39], s[0:1]
	s_cbranch_execz .LBB0_683
	s_waitcnt lgkmcnt(0)
	v_add_f32_e32 v64, v64, v65
	global_atomic_add_f32 v[180:181], v64, off offset:192
.LBB0_683:
	s_or_b64 exec, exec, s[38:39]
	v_lshl_add_u64 v[182:183], v[182:183], 0, s[16:17]
	s_waitcnt vmcnt(0)
	v_pk_add_f32 v[94:95], v[62:63], v[94:95]
	v_pk_add_f32 v[92:93], v[60:61], v[92:93]
	v_pk_add_f32 v[90:91], v[58:59], v[90:91]
	flat_load_dwordx4 v[76:79], v[182:183] nt
	flat_load_dwordx4 v[72:75], v[182:183] offset:16 nt
	flat_load_dwordx4 v[68:71], v[182:183] offset:512 nt
	s_waitcnt lgkmcnt(0)
	flat_load_dwordx4 v[64:67], v[182:183] offset:528 nt
	v_pk_add_f32 v[88:89], v[56:57], v[88:89]
	v_mul_f32_e32 v60, v93, v93
	v_mul_f32_e32 v61, v95, v95
	v_mul_f32_e32 v56, v89, v89
	v_mul_f32_e32 v57, v91, v91
	v_pk_add_f32 v[86:87], v[54:55], v[86:87]
	v_pk_add_f32 v[84:85], v[52:53], v[84:85]
	v_fmac_f32_e32 v60, v92, v92
	v_fmac_f32_e32 v61, v94, v94
	v_fmac_f32_e32 v56, v88, v88
	v_fmac_f32_e32 v57, v90, v90
	v_mul_f32_e32 v52, v85, v85
	v_mul_f32_e32 v53, v87, v87
	v_pk_add_f32 v[82:83], v[50:51], v[82:83]
	v_pk_add_f32 v[80:81], v[48:49], v[80:81]
	v_add_f32_e32 v60, v60, v61
	v_add_f32_e32 v56, v56, v57
	v_fmac_f32_e32 v52, v84, v84
	v_fmac_f32_e32 v53, v86, v86
	v_mul_f32_e32 v48, v81, v81
	v_mul_f32_e32 v49, v83, v83
	v_add_f32_e32 v56, v60, v56
	v_add_f32_e32 v52, v52, v53
	v_fmac_f32_e32 v48, v80, v80
	v_fmac_f32_e32 v49, v82, v82
	v_add_f32_e32 v52, v56, v52
	v_add_f32_e32 v48, v48, v49
	v_add_f32_e32 v48, v52, v48
	ds_bpermute_b32 v49, v191, v48
	s_waitcnt lgkmcnt(0)
	v_add_f32_e32 v48, v48, v49
	ds_bpermute_b32 v49, v192, v48
	s_and_saveexec_b64 s[38:39], s[0:1]
	s_cbranch_execz .LBB0_685
	s_waitcnt lgkmcnt(0)
	v_add_f32_e32 v48, v48, v49
	global_atomic_add_f32 v[180:181], v48, off offset:512
.LBB0_685:
	s_or_b64 exec, exec, s[38:39]
	v_lshl_add_u64 v[182:183], v[182:183], 0, s[16:17]
	s_waitcnt vmcnt(0)
	v_pk_add_f32 v[78:79], v[46:47], v[78:79]
	v_pk_add_f32 v[76:77], v[44:45], v[76:77]
	v_pk_add_f32 v[74:75], v[42:43], v[74:75]
	flat_load_dwordx4 v[60:63], v[182:183] nt
	flat_load_dwordx4 v[56:59], v[182:183] offset:16 nt
	flat_load_dwordx4 v[52:55], v[182:183] offset:512 nt
	s_waitcnt lgkmcnt(0)
	flat_load_dwordx4 v[48:51], v[182:183] offset:528 nt
	v_pk_add_f32 v[72:73], v[40:41], v[72:73]
	v_mul_f32_e32 v44, v77, v77
	v_mul_f32_e32 v45, v79, v79
	v_mul_f32_e32 v40, v73, v73
	v_mul_f32_e32 v41, v75, v75
	v_pk_add_f32 v[70:71], v[38:39], v[70:71]
	v_pk_add_f32 v[68:69], v[36:37], v[68:69]
	v_fmac_f32_e32 v44, v76, v76
	v_fmac_f32_e32 v45, v78, v78
	v_fmac_f32_e32 v40, v72, v72
	v_fmac_f32_e32 v41, v74, v74
	v_mul_f32_e32 v36, v69, v69
	v_mul_f32_e32 v37, v71, v71
	v_pk_add_f32 v[66:67], v[34:35], v[66:67]
	v_pk_add_f32 v[64:65], v[32:33], v[64:65]
	v_add_f32_e32 v44, v44, v45
	v_add_f32_e32 v40, v40, v41
	v_fmac_f32_e32 v36, v68, v68
	v_fmac_f32_e32 v37, v70, v70
	v_mul_f32_e32 v32, v65, v65
	v_mul_f32_e32 v33, v67, v67
	v_add_f32_e32 v40, v44, v40
	v_add_f32_e32 v36, v36, v37
	v_fmac_f32_e32 v32, v64, v64
	v_fmac_f32_e32 v33, v66, v66
	v_add_f32_e32 v36, v40, v36
	v_add_f32_e32 v32, v32, v33
	v_add_f32_e32 v32, v36, v32
	ds_bpermute_b32 v33, v191, v32
	s_waitcnt lgkmcnt(0)
	v_add_f32_e32 v32, v32, v33
	ds_bpermute_b32 v33, v192, v32
	s_and_saveexec_b64 s[38:39], s[0:1]
	s_cbranch_execz .LBB0_687
	s_waitcnt lgkmcnt(0)
	v_add_f32_e32 v32, v32, v33
	global_atomic_add_f32 v[180:181], v32, off offset:576
.LBB0_687:
	s_or_b64 exec, exec, s[38:39]
	v_lshl_add_u64 v[182:183], v[182:183], 0, s[16:17]
	s_waitcnt vmcnt(0)
	v_pk_add_f32 v[62:63], v[30:31], v[62:63]
	v_pk_add_f32 v[60:61], v[28:29], v[60:61]
	v_pk_add_f32 v[58:59], v[26:27], v[58:59]
	flat_load_dwordx4 v[44:47], v[182:183] nt
	flat_load_dwordx4 v[40:43], v[182:183] offset:16 nt
	flat_load_dwordx4 v[36:39], v[182:183] offset:512 nt
	s_waitcnt lgkmcnt(0)
	flat_load_dwordx4 v[32:35], v[182:183] offset:528 nt
	v_pk_add_f32 v[56:57], v[24:25], v[56:57]
	v_mul_f32_e32 v28, v61, v61
	v_mul_f32_e32 v29, v63, v63
	v_mul_f32_e32 v24, v57, v57
	v_mul_f32_e32 v25, v59, v59
	v_pk_add_f32 v[54:55], v[22:23], v[54:55]
	v_pk_add_f32 v[52:53], v[20:21], v[52:53]
	v_fmac_f32_e32 v28, v60, v60
	v_fmac_f32_e32 v29, v62, v62
	v_fmac_f32_e32 v24, v56, v56
	v_fmac_f32_e32 v25, v58, v58
	v_mul_f32_e32 v20, v53, v53
	v_mul_f32_e32 v21, v55, v55
	v_add_f32_e32 v28, v28, v29
	v_add_f32_e32 v24, v24, v25
	v_fmac_f32_e32 v20, v52, v52
	v_fmac_f32_e32 v21, v54, v54
	v_add_f32_e32 v24, v28, v24
	v_add_f32_e32 v20, v20, v21
	v_add_f32_e32 v20, v24, v20
	v_pk_add_f32 v[24:25], v[18:19], v[50:51]
	v_pk_add_f32 v[48:49], v[16:17], v[48:49]
	v_mul_f32_e32 v17, v25, v25
	v_mul_f32_e32 v16, v49, v49
	v_fmac_f32_e32 v16, v48, v48
	v_fmac_f32_e32 v17, v24, v24
	v_add_f32_e32 v16, v16, v17
	v_add_f32_e32 v16, v20, v16
	ds_bpermute_b32 v17, v191, v16
	s_waitcnt lgkmcnt(0)
	v_add_f32_e32 v16, v16, v17
	ds_bpermute_b32 v17, v192, v16
	s_and_saveexec_b64 s[38:39], s[0:1]
	s_cbranch_execz .LBB0_689
	s_waitcnt lgkmcnt(0)
	v_add_f32_e32 v16, v16, v17
	global_atomic_add_f32 v[180:181], v16, off offset:640
